# prologue mod GEMV K loop hand-written: 48 loads in flight per wave, pk_fma f32 accumulate (was 8 in flight, 16 serialized round trips)
# speedup vs baseline: 1.0097x; 1.0044x over previous
.LBB0_1070:
	s_mul_hi_i32 s24, s3, 0x38e38e39
	s_lshr_b32 s25, s24, 31
	s_ashr_i32 s28, s24, 5
	s_add_i32 s28, s28, s25
	s_mul_i32 s24, s28, 0x90
	s_sub_i32 s24, s3, s24
	s_lshl_b32 s24, s24, 6
	s_ashr_i32 s25, s24, 31
	s_mul_i32 s31, s28, 0x2400000
	s_lshl_b64 s[26:27], s[24:25], 2
	s_mul_hi_i32 s30, s28, 0x2400000
	s_add_u32 s26, s31, s26
	s_addc_u32 s27, s30, s27
	v_lshl_add_u64 v[12:13], v[10:11], 0, s[26:27]
	v_mov_b32_e32 v26, s0
	v_readfirstlane_b32 s98, v12
	v_readfirstlane_b32 s99, v13
	v_mov_b32_e32 v14, 0
	v_mov_b32_e32 v15, 0
	v_mov_b32_e32 v16, 0
	v_mov_b32_e32 v17, 0
	v_mov_b32_e32 v18, 0
	v_mov_b32_e32 v19, 0
	v_mov_b32_e32 v20, 0
	v_mov_b32_e32 v21, 0
	v_mov_b32_e32 v22, 0
	v_mov_b32_e32 v23, 0
	v_mov_b32_e32 v24, 0
	v_mov_b32_e32 v25, 0
	v_mov_b32_e32 v30, 0
	v_mov_b32_e32 v31, 0
	v_mov_b32_e32 v34, 0
	v_mov_b32_e32 v35, 0
	v_mov_b32_e32 v38, 0
	v_mov_b32_e32 v39, 0
	s_sub_u32 s98, s98, 0x87000
	s_subb_u32 s99, s99, 0
	global_load_dword v64, v27, s[98:99] nt
	s_add_u32 s98, s98, 0x9000
	s_addc_u32 s99, s99, 0
	global_load_dword v65, v27, s[98:99] nt
	s_add_u32 s98, s98, 0x9000
	s_addc_u32 s99, s99, 0
	global_load_dword v66, v27, s[98:99] nt
	s_add_u32 s98, s98, 0x9000
	s_addc_u32 s99, s99, 0
	global_load_dword v67, v27, s[98:99] nt
	s_add_u32 s98, s98, 0x9000
	s_addc_u32 s99, s99, 0
	global_load_dword v68, v27, s[98:99] nt
	s_add_u32 s98, s98, 0x9000
	s_addc_u32 s99, s99, 0
	global_load_dword v69, v27, s[98:99] nt
	s_add_u32 s98, s98, 0x9000
	s_addc_u32 s99, s99, 0
	global_load_dword v70, v27, s[98:99] nt
	s_add_u32 s98, s98, 0x9000
	s_addc_u32 s99, s99, 0
	global_load_dword v71, v27, s[98:99] nt
	s_add_u32 s98, s98, 0x9000
	s_addc_u32 s99, s99, 0
	global_load_dword v72, v27, s[98:99] nt
	s_add_u32 s98, s98, 0x9000
	s_addc_u32 s99, s99, 0
	global_load_dword v73, v27, s[98:99] nt
	s_add_u32 s98, s98, 0x9000
	s_addc_u32 s99, s99, 0
	global_load_dword v74, v27, s[98:99] nt
	s_add_u32 s98, s98, 0x9000
	s_addc_u32 s99, s99, 0
	global_load_dword v75, v27, s[98:99] nt
	s_add_u32 s98, s98, 0x9000
	s_addc_u32 s99, s99, 0
	global_load_dword v76, v27, s[98:99] nt
	s_add_u32 s98, s98, 0x9000
	s_addc_u32 s99, s99, 0
	global_load_dword v77, v27, s[98:99] nt
	s_add_u32 s98, s98, 0x9000
	s_addc_u32 s99, s99, 0
	global_load_dword v78, v27, s[98:99] nt
	s_add_u32 s98, s98, 0x9000
	s_addc_u32 s99, s99, 0
	global_load_dword v79, v27, s[98:99] nt
	s_add_u32 s98, s98, 0x9000
	s_addc_u32 s99, s99, 0
	global_load_dword v80, v27, s[98:99] nt
	s_add_u32 s98, s98, 0x9000
	s_addc_u32 s99, s99, 0
	global_load_dword v81, v27, s[98:99] nt
	s_add_u32 s98, s98, 0x9000
	s_addc_u32 s99, s99, 0
	global_load_dword v82, v27, s[98:99] nt
	s_add_u32 s98, s98, 0x9000
	s_addc_u32 s99, s99, 0
	global_load_dword v83, v27, s[98:99] nt
	s_add_u32 s98, s98, 0x9000
	s_addc_u32 s99, s99, 0
	global_load_dword v84, v27, s[98:99] nt
	s_add_u32 s98, s98, 0x9000
	s_addc_u32 s99, s99, 0
	global_load_dword v85, v27, s[98:99] nt
	s_add_u32 s98, s98, 0x9000
	s_addc_u32 s99, s99, 0
	global_load_dword v86, v27, s[98:99] nt
	s_add_u32 s98, s98, 0x9000
	s_addc_u32 s99, s99, 0
	global_load_dword v87, v27, s[98:99] nt
	s_add_u32 s98, s98, 0x9000
	s_addc_u32 s99, s99, 0
	global_load_dword v88, v27, s[98:99] nt
	s_add_u32 s98, s98, 0x9000
	s_addc_u32 s99, s99, 0
	global_load_dword v89, v27, s[98:99] nt
	s_add_u32 s98, s98, 0x9000
	s_addc_u32 s99, s99, 0
	global_load_dword v90, v27, s[98:99] nt
	s_add_u32 s98, s98, 0x9000
	s_addc_u32 s99, s99, 0
	global_load_dword v91, v27, s[98:99] nt
	s_add_u32 s98, s98, 0x9000
	s_addc_u32 s99, s99, 0
	global_load_dword v92, v27, s[98:99] nt
	s_add_u32 s98, s98, 0x9000
	s_addc_u32 s99, s99, 0
	global_load_dword v93, v27, s[98:99] nt
	s_add_u32 s98, s98, 0x9000
	s_addc_u32 s99, s99, 0
	global_load_dword v94, v27, s[98:99] nt
	s_add_u32 s98, s98, 0x9000
	s_addc_u32 s99, s99, 0
	global_load_dword v95, v27, s[98:99] nt
	s_add_u32 s98, s98, 0x9000
	s_addc_u32 s99, s99, 0
	global_load_dword v96, v27, s[98:99] nt
	s_add_u32 s98, s98, 0x9000
	s_addc_u32 s99, s99, 0
	global_load_dword v97, v27, s[98:99] nt
	s_add_u32 s98, s98, 0x9000
	s_addc_u32 s99, s99, 0
	global_load_dword v98, v27, s[98:99] nt
	s_add_u32 s98, s98, 0x9000
	s_addc_u32 s99, s99, 0
	global_load_dword v99, v27, s[98:99] nt
	s_add_u32 s98, s98, 0x9000
	s_addc_u32 s99, s99, 0
	global_load_dword v100, v27, s[98:99] nt
	s_add_u32 s98, s98, 0x9000
	s_addc_u32 s99, s99, 0
	global_load_dword v101, v27, s[98:99] nt
	s_add_u32 s98, s98, 0x9000
	s_addc_u32 s99, s99, 0
	global_load_dword v102, v27, s[98:99] nt
	s_add_u32 s98, s98, 0x9000
	s_addc_u32 s99, s99, 0
	global_load_dword v103, v27, s[98:99] nt
	s_add_u32 s98, s98, 0x9000
	s_addc_u32 s99, s99, 0
	global_load_dword v104, v27, s[98:99] nt
	s_add_u32 s98, s98, 0x9000
	s_addc_u32 s99, s99, 0
	global_load_dword v105, v27, s[98:99] nt
	s_add_u32 s98, s98, 0x9000
	s_addc_u32 s99, s99, 0
	global_load_dword v106, v27, s[98:99] nt
	s_add_u32 s98, s98, 0x9000
	s_addc_u32 s99, s99, 0
	global_load_dword v107, v27, s[98:99] nt
	s_add_u32 s98, s98, 0x9000
	s_addc_u32 s99, s99, 0
	global_load_dword v108, v27, s[98:99] nt
	s_add_u32 s98, s98, 0x9000
	s_addc_u32 s99, s99, 0
	global_load_dword v109, v27, s[98:99] nt
	s_add_u32 s98, s98, 0x9000
	s_addc_u32 s99, s99, 0
	global_load_dword v110, v27, s[98:99] nt
	s_add_u32 s98, s98, 0x9000
	s_addc_u32 s99, s99, 0
	global_load_dword v111, v27, s[98:99] nt
	s_add_u32 s98, s98, 0x9000
	s_addc_u32 s99, s99, 0
	ds_read_b128 v[40:43], v26
	ds_read_b128 v[44:47], v26 offset:16
	ds_read_b128 v[48:51], v26 offset:32
	ds_read_b128 v[52:55], v26 offset:48
	ds_read_b128 v[160:163], v26 offset:4096
	ds_read_b128 v[164:167], v26 offset:4112
	ds_read_b128 v[168:171], v26 offset:4128
	ds_read_b128 v[172:175], v26 offset:4144
	ds_read_b128 v[0:3], v26 offset:8192
	ds_read_b128 v[4:7], v26 offset:8208
	ds_read_b128 v[56:59], v26 offset:8224
	ds_read_b128 v[60:63], v26 offset:8240
	s_waitcnt vmcnt(32) lgkmcnt(8)
	v_pk_fma_f32 v[14:15], v[64:65], v[40:41], v[14:15]
	v_pk_fma_f32 v[14:15], v[66:67], v[42:43], v[14:15]
	v_pk_fma_f32 v[14:15], v[68:69], v[44:45], v[14:15]
	v_pk_fma_f32 v[14:15], v[70:71], v[46:47], v[14:15]
	v_pk_fma_f32 v[14:15], v[72:73], v[48:49], v[14:15]
	v_pk_fma_f32 v[14:15], v[74:75], v[50:51], v[14:15]
	v_pk_fma_f32 v[14:15], v[76:77], v[52:53], v[14:15]
	v_pk_fma_f32 v[14:15], v[78:79], v[54:55], v[14:15]
	global_load_dword v112, v27, s[98:99] nt
	s_add_u32 s98, s98, 0x9000
	s_addc_u32 s99, s99, 0
	global_load_dword v113, v27, s[98:99] nt
	s_add_u32 s98, s98, 0x9000
	s_addc_u32 s99, s99, 0
	global_load_dword v114, v27, s[98:99] nt
	s_add_u32 s98, s98, 0x9000
	s_addc_u32 s99, s99, 0
	global_load_dword v115, v27, s[98:99] nt
	s_add_u32 s98, s98, 0x9000
	s_addc_u32 s99, s99, 0
	global_load_dword v116, v27, s[98:99] nt
	s_add_u32 s98, s98, 0x9000
	s_addc_u32 s99, s99, 0
	global_load_dword v117, v27, s[98:99] nt
	s_add_u32 s98, s98, 0x9000
	s_addc_u32 s99, s99, 0
	global_load_dword v118, v27, s[98:99] nt
	s_add_u32 s98, s98, 0x9000
	s_addc_u32 s99, s99, 0
	global_load_dword v119, v27, s[98:99] nt
	s_add_u32 s98, s98, 0x9000
	s_addc_u32 s99, s99, 0
	global_load_dword v120, v27, s[98:99] nt
	s_add_u32 s98, s98, 0x9000
	s_addc_u32 s99, s99, 0
	global_load_dword v121, v27, s[98:99] nt
	s_add_u32 s98, s98, 0x9000
	s_addc_u32 s99, s99, 0
	global_load_dword v122, v27, s[98:99] nt
	s_add_u32 s98, s98, 0x9000
	s_addc_u32 s99, s99, 0
	global_load_dword v123, v27, s[98:99] nt
	s_add_u32 s98, s98, 0x9000
	s_addc_u32 s99, s99, 0
	global_load_dword v124, v27, s[98:99] nt
	s_add_u32 s98, s98, 0x9000
	s_addc_u32 s99, s99, 0
	global_load_dword v125, v27, s[98:99] nt
	s_add_u32 s98, s98, 0x9000
	s_addc_u32 s99, s99, 0
	global_load_dword v126, v27, s[98:99] nt
	s_add_u32 s98, s98, 0x9000
	s_addc_u32 s99, s99, 0
	global_load_dword v127, v27, s[98:99] nt
	s_add_u32 s98, s98, 0x9000
	s_addc_u32 s99, s99, 0
	ds_read_b128 v[40:43], v26 offset:12288
	ds_read_b128 v[44:47], v26 offset:12304
	ds_read_b128 v[48:51], v26 offset:12320
	ds_read_b128 v[52:55], v26 offset:12336
	s_waitcnt lgkmcnt(8)
	v_pk_fma_f32 v[16:17], v[64:65], v[160:161], v[16:17]
	v_pk_fma_f32 v[16:17], v[66:67], v[162:163], v[16:17]
	v_pk_fma_f32 v[16:17], v[68:69], v[164:165], v[16:17]
	v_pk_fma_f32 v[16:17], v[70:71], v[166:167], v[16:17]
	v_pk_fma_f32 v[16:17], v[72:73], v[168:169], v[16:17]
	v_pk_fma_f32 v[16:17], v[74:75], v[170:171], v[16:17]
	v_pk_fma_f32 v[16:17], v[76:77], v[172:173], v[16:17]
	v_pk_fma_f32 v[16:17], v[78:79], v[174:175], v[16:17]
	ds_read_b128 v[160:163], v26 offset:16384
	ds_read_b128 v[164:167], v26 offset:16400
	ds_read_b128 v[168:171], v26 offset:16416
	ds_read_b128 v[172:175], v26 offset:16432
	s_waitcnt lgkmcnt(8)
	v_pk_fma_f32 v[18:19], v[64:65], v[0:1], v[18:19]
	v_pk_fma_f32 v[18:19], v[66:67], v[2:3], v[18:19]
	v_pk_fma_f32 v[18:19], v[68:69], v[4:5], v[18:19]
	v_pk_fma_f32 v[18:19], v[70:71], v[6:7], v[18:19]
	v_pk_fma_f32 v[18:19], v[72:73], v[56:57], v[18:19]
	v_pk_fma_f32 v[18:19], v[74:75], v[58:59], v[18:19]
	v_pk_fma_f32 v[18:19], v[76:77], v[60:61], v[18:19]
	v_pk_fma_f32 v[18:19], v[78:79], v[62:63], v[18:19]
	ds_read_b128 v[0:3], v26 offset:20480
	ds_read_b128 v[4:7], v26 offset:20496
	ds_read_b128 v[56:59], v26 offset:20512
	ds_read_b128 v[60:63], v26 offset:20528
	s_waitcnt lgkmcnt(8)
	v_pk_fma_f32 v[20:21], v[64:65], v[40:41], v[20:21]
	v_pk_fma_f32 v[20:21], v[66:67], v[42:43], v[20:21]
	v_pk_fma_f32 v[20:21], v[68:69], v[44:45], v[20:21]
	v_pk_fma_f32 v[20:21], v[70:71], v[46:47], v[20:21]
	v_pk_fma_f32 v[20:21], v[72:73], v[48:49], v[20:21]
	v_pk_fma_f32 v[20:21], v[74:75], v[50:51], v[20:21]
	v_pk_fma_f32 v[20:21], v[76:77], v[52:53], v[20:21]
	v_pk_fma_f32 v[20:21], v[78:79], v[54:55], v[20:21]
	ds_read_b128 v[40:43], v26 offset:24576
	ds_read_b128 v[44:47], v26 offset:24592
	ds_read_b128 v[48:51], v26 offset:24608
	ds_read_b128 v[52:55], v26 offset:24624
	s_waitcnt lgkmcnt(8)
	v_pk_fma_f32 v[22:23], v[64:65], v[160:161], v[22:23]
	v_pk_fma_f32 v[22:23], v[66:67], v[162:163], v[22:23]
	v_pk_fma_f32 v[22:23], v[68:69], v[164:165], v[22:23]
	v_pk_fma_f32 v[22:23], v[70:71], v[166:167], v[22:23]
	v_pk_fma_f32 v[22:23], v[72:73], v[168:169], v[22:23]
	v_pk_fma_f32 v[22:23], v[74:75], v[170:171], v[22:23]
	v_pk_fma_f32 v[22:23], v[76:77], v[172:173], v[22:23]
	v_pk_fma_f32 v[22:23], v[78:79], v[174:175], v[22:23]
	ds_read_b128 v[160:163], v26 offset:28672
	ds_read_b128 v[164:167], v26 offset:28688
	ds_read_b128 v[168:171], v26 offset:28704
	ds_read_b128 v[172:175], v26 offset:28720
	s_waitcnt lgkmcnt(8)
	v_pk_fma_f32 v[24:25], v[64:65], v[0:1], v[24:25]
	v_pk_fma_f32 v[24:25], v[66:67], v[2:3], v[24:25]
	v_pk_fma_f32 v[24:25], v[68:69], v[4:5], v[24:25]
	v_pk_fma_f32 v[24:25], v[70:71], v[6:7], v[24:25]
	v_pk_fma_f32 v[24:25], v[72:73], v[56:57], v[24:25]
	v_pk_fma_f32 v[24:25], v[74:75], v[58:59], v[24:25]
	v_pk_fma_f32 v[24:25], v[76:77], v[60:61], v[24:25]
	v_pk_fma_f32 v[24:25], v[78:79], v[62:63], v[24:25]
	ds_read_b128 v[0:3], v26 offset:32768
	ds_read_b128 v[4:7], v26 offset:32784
	ds_read_b128 v[56:59], v26 offset:32800
	ds_read_b128 v[60:63], v26 offset:32816
	s_waitcnt lgkmcnt(8)
	v_pk_fma_f32 v[30:31], v[64:65], v[40:41], v[30:31]
	v_pk_fma_f32 v[30:31], v[66:67], v[42:43], v[30:31]
	v_pk_fma_f32 v[30:31], v[68:69], v[44:45], v[30:31]
	v_pk_fma_f32 v[30:31], v[70:71], v[46:47], v[30:31]
	v_pk_fma_f32 v[30:31], v[72:73], v[48:49], v[30:31]
	v_pk_fma_f32 v[30:31], v[74:75], v[50:51], v[30:31]
	v_pk_fma_f32 v[30:31], v[76:77], v[52:53], v[30:31]
	v_pk_fma_f32 v[30:31], v[78:79], v[54:55], v[30:31]
	ds_read_b128 v[40:43], v26 offset:64
	ds_read_b128 v[44:47], v26 offset:80
	ds_read_b128 v[48:51], v26 offset:96
	ds_read_b128 v[52:55], v26 offset:112
	s_waitcnt lgkmcnt(8)
	v_pk_fma_f32 v[34:35], v[64:65], v[160:161], v[34:35]
	v_pk_fma_f32 v[34:35], v[66:67], v[162:163], v[34:35]
	v_pk_fma_f32 v[34:35], v[68:69], v[164:165], v[34:35]
	v_pk_fma_f32 v[34:35], v[70:71], v[166:167], v[34:35]
	v_pk_fma_f32 v[34:35], v[72:73], v[168:169], v[34:35]
	v_pk_fma_f32 v[34:35], v[74:75], v[170:171], v[34:35]
	v_pk_fma_f32 v[34:35], v[76:77], v[172:173], v[34:35]
	v_pk_fma_f32 v[34:35], v[78:79], v[174:175], v[34:35]
	ds_read_b128 v[160:163], v26 offset:4160
	ds_read_b128 v[164:167], v26 offset:4176
	ds_read_b128 v[168:171], v26 offset:4192
	ds_read_b128 v[172:175], v26 offset:4208
	s_waitcnt lgkmcnt(8)
	v_pk_fma_f32 v[38:39], v[64:65], v[0:1], v[38:39]
	v_pk_fma_f32 v[38:39], v[66:67], v[2:3], v[38:39]
	v_pk_fma_f32 v[38:39], v[68:69], v[4:5], v[38:39]
	v_pk_fma_f32 v[38:39], v[70:71], v[6:7], v[38:39]
	v_pk_fma_f32 v[38:39], v[72:73], v[56:57], v[38:39]
	v_pk_fma_f32 v[38:39], v[74:75], v[58:59], v[38:39]
	v_pk_fma_f32 v[38:39], v[76:77], v[60:61], v[38:39]
	v_pk_fma_f32 v[38:39], v[78:79], v[62:63], v[38:39]
	ds_read_b128 v[0:3], v26 offset:8256
	ds_read_b128 v[4:7], v26 offset:8272
	ds_read_b128 v[56:59], v26 offset:8288
	ds_read_b128 v[60:63], v26 offset:8304
	s_waitcnt vmcnt(32) lgkmcnt(8)
	v_pk_fma_f32 v[14:15], v[80:81], v[40:41], v[14:15]
	v_pk_fma_f32 v[14:15], v[82:83], v[42:43], v[14:15]
	v_pk_fma_f32 v[14:15], v[84:85], v[44:45], v[14:15]
	v_pk_fma_f32 v[14:15], v[86:87], v[46:47], v[14:15]
	v_pk_fma_f32 v[14:15], v[88:89], v[48:49], v[14:15]
	v_pk_fma_f32 v[14:15], v[90:91], v[50:51], v[14:15]
	v_pk_fma_f32 v[14:15], v[92:93], v[52:53], v[14:15]
	v_pk_fma_f32 v[14:15], v[94:95], v[54:55], v[14:15]
	global_load_dword v64, v27, s[98:99] nt
	s_add_u32 s98, s98, 0x9000
	s_addc_u32 s99, s99, 0
	global_load_dword v65, v27, s[98:99] nt
	s_add_u32 s98, s98, 0x9000
	s_addc_u32 s99, s99, 0
	global_load_dword v66, v27, s[98:99] nt
	s_add_u32 s98, s98, 0x9000
	s_addc_u32 s99, s99, 0
	global_load_dword v67, v27, s[98:99] nt
	s_add_u32 s98, s98, 0x9000
	s_addc_u32 s99, s99, 0
	global_load_dword v68, v27, s[98:99] nt
	s_add_u32 s98, s98, 0x9000
	s_addc_u32 s99, s99, 0
	global_load_dword v69, v27, s[98:99] nt
	s_add_u32 s98, s98, 0x9000
	s_addc_u32 s99, s99, 0
	global_load_dword v70, v27, s[98:99] nt
	s_add_u32 s98, s98, 0x9000
	s_addc_u32 s99, s99, 0
	global_load_dword v71, v27, s[98:99] nt
	s_add_u32 s98, s98, 0x9000
	s_addc_u32 s99, s99, 0
	global_load_dword v72, v27, s[98:99] nt
	s_add_u32 s98, s98, 0x9000
	s_addc_u32 s99, s99, 0
	global_load_dword v73, v27, s[98:99] nt
	s_add_u32 s98, s98, 0x9000
	s_addc_u32 s99, s99, 0
	global_load_dword v74, v27, s[98:99] nt
	s_add_u32 s98, s98, 0x9000
	s_addc_u32 s99, s99, 0
	global_load_dword v75, v27, s[98:99] nt
	s_add_u32 s98, s98, 0x9000
	s_addc_u32 s99, s99, 0
	global_load_dword v76, v27, s[98:99] nt
	s_add_u32 s98, s98, 0x9000
	s_addc_u32 s99, s99, 0
	global_load_dword v77, v27, s[98:99] nt
	s_add_u32 s98, s98, 0x9000
	s_addc_u32 s99, s99, 0
	global_load_dword v78, v27, s[98:99] nt
	s_add_u32 s98, s98, 0x9000
	s_addc_u32 s99, s99, 0
	global_load_dword v79, v27, s[98:99] nt
	s_add_u32 s98, s98, 0x9000
	s_addc_u32 s99, s99, 0
	ds_read_b128 v[40:43], v26 offset:12352
	ds_read_b128 v[44:47], v26 offset:12368
	ds_read_b128 v[48:51], v26 offset:12384
	ds_read_b128 v[52:55], v26 offset:12400
	s_waitcnt lgkmcnt(8)
	v_pk_fma_f32 v[16:17], v[80:81], v[160:161], v[16:17]
	v_pk_fma_f32 v[16:17], v[82:83], v[162:163], v[16:17]
	v_pk_fma_f32 v[16:17], v[84:85], v[164:165], v[16:17]
	v_pk_fma_f32 v[16:17], v[86:87], v[166:167], v[16:17]
	v_pk_fma_f32 v[16:17], v[88:89], v[168:169], v[16:17]
	v_pk_fma_f32 v[16:17], v[90:91], v[170:171], v[16:17]
	v_pk_fma_f32 v[16:17], v[92:93], v[172:173], v[16:17]
	v_pk_fma_f32 v[16:17], v[94:95], v[174:175], v[16:17]
	ds_read_b128 v[160:163], v26 offset:16448
	ds_read_b128 v[164:167], v26 offset:16464
	ds_read_b128 v[168:171], v26 offset:16480
	ds_read_b128 v[172:175], v26 offset:16496
	s_waitcnt lgkmcnt(8)
	v_pk_fma_f32 v[18:19], v[80:81], v[0:1], v[18:19]
	v_pk_fma_f32 v[18:19], v[82:83], v[2:3], v[18:19]
	v_pk_fma_f32 v[18:19], v[84:85], v[4:5], v[18:19]
	v_pk_fma_f32 v[18:19], v[86:87], v[6:7], v[18:19]
	v_pk_fma_f32 v[18:19], v[88:89], v[56:57], v[18:19]
	v_pk_fma_f32 v[18:19], v[90:91], v[58:59], v[18:19]
	v_pk_fma_f32 v[18:19], v[92:93], v[60:61], v[18:19]
	v_pk_fma_f32 v[18:19], v[94:95], v[62:63], v[18:19]
	ds_read_b128 v[0:3], v26 offset:20544
	ds_read_b128 v[4:7], v26 offset:20560
	ds_read_b128 v[56:59], v26 offset:20576
	ds_read_b128 v[60:63], v26 offset:20592
	s_waitcnt lgkmcnt(8)
	v_pk_fma_f32 v[20:21], v[80:81], v[40:41], v[20:21]
	v_pk_fma_f32 v[20:21], v[82:83], v[42:43], v[20:21]
	v_pk_fma_f32 v[20:21], v[84:85], v[44:45], v[20:21]
	v_pk_fma_f32 v[20:21], v[86:87], v[46:47], v[20:21]
	v_pk_fma_f32 v[20:21], v[88:89], v[48:49], v[20:21]
	v_pk_fma_f32 v[20:21], v[90:91], v[50:51], v[20:21]
	v_pk_fma_f32 v[20:21], v[92:93], v[52:53], v[20:21]
	v_pk_fma_f32 v[20:21], v[94:95], v[54:55], v[20:21]
	ds_read_b128 v[40:43], v26 offset:24640
	ds_read_b128 v[44:47], v26 offset:24656
	ds_read_b128 v[48:51], v26 offset:24672
	ds_read_b128 v[52:55], v26 offset:24688
	s_waitcnt lgkmcnt(8)
	v_pk_fma_f32 v[22:23], v[80:81], v[160:161], v[22:23]
	v_pk_fma_f32 v[22:23], v[82:83], v[162:163], v[22:23]
	v_pk_fma_f32 v[22:23], v[84:85], v[164:165], v[22:23]
	v_pk_fma_f32 v[22:23], v[86:87], v[166:167], v[22:23]
	v_pk_fma_f32 v[22:23], v[88:89], v[168:169], v[22:23]
	v_pk_fma_f32 v[22:23], v[90:91], v[170:171], v[22:23]
	v_pk_fma_f32 v[22:23], v[92:93], v[172:173], v[22:23]
	v_pk_fma_f32 v[22:23], v[94:95], v[174:175], v[22:23]
	ds_read_b128 v[160:163], v26 offset:28736
	ds_read_b128 v[164:167], v26 offset:28752
	ds_read_b128 v[168:171], v26 offset:28768
	ds_read_b128 v[172:175], v26 offset:28784
	s_waitcnt lgkmcnt(8)
	v_pk_fma_f32 v[24:25], v[80:81], v[0:1], v[24:25]
	v_pk_fma_f32 v[24:25], v[82:83], v[2:3], v[24:25]
	v_pk_fma_f32 v[24:25], v[84:85], v[4:5], v[24:25]
	v_pk_fma_f32 v[24:25], v[86:87], v[6:7], v[24:25]
	v_pk_fma_f32 v[24:25], v[88:89], v[56:57], v[24:25]
	v_pk_fma_f32 v[24:25], v[90:91], v[58:59], v[24:25]
	v_pk_fma_f32 v[24:25], v[92:93], v[60:61], v[24:25]
	v_pk_fma_f32 v[24:25], v[94:95], v[62:63], v[24:25]
	ds_read_b128 v[0:3], v26 offset:32832
	ds_read_b128 v[4:7], v26 offset:32848
	ds_read_b128 v[56:59], v26 offset:32864
	ds_read_b128 v[60:63], v26 offset:32880
	s_waitcnt lgkmcnt(8)
	v_pk_fma_f32 v[30:31], v[80:81], v[40:41], v[30:31]
	v_pk_fma_f32 v[30:31], v[82:83], v[42:43], v[30:31]
	v_pk_fma_f32 v[30:31], v[84:85], v[44:45], v[30:31]
	v_pk_fma_f32 v[30:31], v[86:87], v[46:47], v[30:31]
	v_pk_fma_f32 v[30:31], v[88:89], v[48:49], v[30:31]
	v_pk_fma_f32 v[30:31], v[90:91], v[50:51], v[30:31]
	v_pk_fma_f32 v[30:31], v[92:93], v[52:53], v[30:31]
	v_pk_fma_f32 v[30:31], v[94:95], v[54:55], v[30:31]
	ds_read_b128 v[40:43], v26 offset:128
	ds_read_b128 v[44:47], v26 offset:144
	ds_read_b128 v[48:51], v26 offset:160
	ds_read_b128 v[52:55], v26 offset:176
	s_waitcnt lgkmcnt(8)
	v_pk_fma_f32 v[34:35], v[80:81], v[160:161], v[34:35]
	v_pk_fma_f32 v[34:35], v[82:83], v[162:163], v[34:35]
	v_pk_fma_f32 v[34:35], v[84:85], v[164:165], v[34:35]
	v_pk_fma_f32 v[34:35], v[86:87], v[166:167], v[34:35]
	v_pk_fma_f32 v[34:35], v[88:89], v[168:169], v[34:35]
	v_pk_fma_f32 v[34:35], v[90:91], v[170:171], v[34:35]
	v_pk_fma_f32 v[34:35], v[92:93], v[172:173], v[34:35]
	v_pk_fma_f32 v[34:35], v[94:95], v[174:175], v[34:35]
	ds_read_b128 v[160:163], v26 offset:4224
	ds_read_b128 v[164:167], v26 offset:4240
	ds_read_b128 v[168:171], v26 offset:4256
	ds_read_b128 v[172:175], v26 offset:4272
	s_waitcnt lgkmcnt(8)
	v_pk_fma_f32 v[38:39], v[80:81], v[0:1], v[38:39]
	v_pk_fma_f32 v[38:39], v[82:83], v[2:3], v[38:39]
	v_pk_fma_f32 v[38:39], v[84:85], v[4:5], v[38:39]
	v_pk_fma_f32 v[38:39], v[86:87], v[6:7], v[38:39]
	v_pk_fma_f32 v[38:39], v[88:89], v[56:57], v[38:39]
	v_pk_fma_f32 v[38:39], v[90:91], v[58:59], v[38:39]
	v_pk_fma_f32 v[38:39], v[92:93], v[60:61], v[38:39]
	v_pk_fma_f32 v[38:39], v[94:95], v[62:63], v[38:39]
	ds_read_b128 v[0:3], v26 offset:8320
	ds_read_b128 v[4:7], v26 offset:8336
	ds_read_b128 v[56:59], v26 offset:8352
	ds_read_b128 v[60:63], v26 offset:8368
	s_waitcnt vmcnt(32) lgkmcnt(8)
	v_pk_fma_f32 v[14:15], v[96:97], v[40:41], v[14:15]
	v_pk_fma_f32 v[14:15], v[98:99], v[42:43], v[14:15]
	v_pk_fma_f32 v[14:15], v[100:101], v[44:45], v[14:15]
	v_pk_fma_f32 v[14:15], v[102:103], v[46:47], v[14:15]
	v_pk_fma_f32 v[14:15], v[104:105], v[48:49], v[14:15]
	v_pk_fma_f32 v[14:15], v[106:107], v[50:51], v[14:15]
	v_pk_fma_f32 v[14:15], v[108:109], v[52:53], v[14:15]
	v_pk_fma_f32 v[14:15], v[110:111], v[54:55], v[14:15]
	global_load_dword v80, v27, s[98:99] nt
	s_add_u32 s98, s98, 0x9000
	s_addc_u32 s99, s99, 0
	global_load_dword v81, v27, s[98:99] nt
	s_add_u32 s98, s98, 0x9000
	s_addc_u32 s99, s99, 0
	global_load_dword v82, v27, s[98:99] nt
	s_add_u32 s98, s98, 0x9000
	s_addc_u32 s99, s99, 0
	global_load_dword v83, v27, s[98:99] nt
	s_add_u32 s98, s98, 0x9000
	s_addc_u32 s99, s99, 0
	global_load_dword v84, v27, s[98:99] nt
	s_add_u32 s98, s98, 0x9000
	s_addc_u32 s99, s99, 0
	global_load_dword v85, v27, s[98:99] nt
	s_add_u32 s98, s98, 0x9000
	s_addc_u32 s99, s99, 0
	global_load_dword v86, v27, s[98:99] nt
	s_add_u32 s98, s98, 0x9000
	s_addc_u32 s99, s99, 0
	global_load_dword v87, v27, s[98:99] nt
	s_add_u32 s98, s98, 0x9000
	s_addc_u32 s99, s99, 0
	global_load_dword v88, v27, s[98:99] nt
	s_add_u32 s98, s98, 0x9000
	s_addc_u32 s99, s99, 0
	global_load_dword v89, v27, s[98:99] nt
	s_add_u32 s98, s98, 0x9000
	s_addc_u32 s99, s99, 0
	global_load_dword v90, v27, s[98:99] nt
	s_add_u32 s98, s98, 0x9000
	s_addc_u32 s99, s99, 0
	global_load_dword v91, v27, s[98:99] nt
	s_add_u32 s98, s98, 0x9000
	s_addc_u32 s99, s99, 0
	global_load_dword v92, v27, s[98:99] nt
	s_add_u32 s98, s98, 0x9000
	s_addc_u32 s99, s99, 0
	global_load_dword v93, v27, s[98:99] nt
	s_add_u32 s98, s98, 0x9000
	s_addc_u32 s99, s99, 0
	global_load_dword v94, v27, s[98:99] nt
	s_add_u32 s98, s98, 0x9000
	s_addc_u32 s99, s99, 0
	global_load_dword v95, v27, s[98:99] nt
	s_add_u32 s98, s98, 0x9000
	s_addc_u32 s99, s99, 0
	ds_read_b128 v[40:43], v26 offset:12416
	ds_read_b128 v[44:47], v26 offset:12432
	ds_read_b128 v[48:51], v26 offset:12448
	ds_read_b128 v[52:55], v26 offset:12464
	s_waitcnt lgkmcnt(8)
	v_pk_fma_f32 v[16:17], v[96:97], v[160:161], v[16:17]
	v_pk_fma_f32 v[16:17], v[98:99], v[162:163], v[16:17]
	v_pk_fma_f32 v[16:17], v[100:101], v[164:165], v[16:17]
	v_pk_fma_f32 v[16:17], v[102:103], v[166:167], v[16:17]
	v_pk_fma_f32 v[16:17], v[104:105], v[168:169], v[16:17]
	v_pk_fma_f32 v[16:17], v[106:107], v[170:171], v[16:17]
	v_pk_fma_f32 v[16:17], v[108:109], v[172:173], v[16:17]
	v_pk_fma_f32 v[16:17], v[110:111], v[174:175], v[16:17]
	ds_read_b128 v[160:163], v26 offset:16512
	ds_read_b128 v[164:167], v26 offset:16528
	ds_read_b128 v[168:171], v26 offset:16544
	ds_read_b128 v[172:175], v26 offset:16560
	s_waitcnt lgkmcnt(8)
	v_pk_fma_f32 v[18:19], v[96:97], v[0:1], v[18:19]
	v_pk_fma_f32 v[18:19], v[98:99], v[2:3], v[18:19]
	v_pk_fma_f32 v[18:19], v[100:101], v[4:5], v[18:19]
	v_pk_fma_f32 v[18:19], v[102:103], v[6:7], v[18:19]
	v_pk_fma_f32 v[18:19], v[104:105], v[56:57], v[18:19]
	v_pk_fma_f32 v[18:19], v[106:107], v[58:59], v[18:19]
	v_pk_fma_f32 v[18:19], v[108:109], v[60:61], v[18:19]
	v_pk_fma_f32 v[18:19], v[110:111], v[62:63], v[18:19]
	ds_read_b128 v[0:3], v26 offset:20608
	ds_read_b128 v[4:7], v26 offset:20624
	ds_read_b128 v[56:59], v26 offset:20640
	ds_read_b128 v[60:63], v26 offset:20656
	s_waitcnt lgkmcnt(8)
	v_pk_fma_f32 v[20:21], v[96:97], v[40:41], v[20:21]
	v_pk_fma_f32 v[20:21], v[98:99], v[42:43], v[20:21]
	v_pk_fma_f32 v[20:21], v[100:101], v[44:45], v[20:21]
	v_pk_fma_f32 v[20:21], v[102:103], v[46:47], v[20:21]
	v_pk_fma_f32 v[20:21], v[104:105], v[48:49], v[20:21]
	v_pk_fma_f32 v[20:21], v[106:107], v[50:51], v[20:21]
	v_pk_fma_f32 v[20:21], v[108:109], v[52:53], v[20:21]
	v_pk_fma_f32 v[20:21], v[110:111], v[54:55], v[20:21]
	ds_read_b128 v[40:43], v26 offset:24704
	ds_read_b128 v[44:47], v26 offset:24720
	ds_read_b128 v[48:51], v26 offset:24736
	ds_read_b128 v[52:55], v26 offset:24752
	s_waitcnt lgkmcnt(8)
	v_pk_fma_f32 v[22:23], v[96:97], v[160:161], v[22:23]
	v_pk_fma_f32 v[22:23], v[98:99], v[162:163], v[22:23]
	v_pk_fma_f32 v[22:23], v[100:101], v[164:165], v[22:23]
	v_pk_fma_f32 v[22:23], v[102:103], v[166:167], v[22:23]
	v_pk_fma_f32 v[22:23], v[104:105], v[168:169], v[22:23]
	v_pk_fma_f32 v[22:23], v[106:107], v[170:171], v[22:23]
	v_pk_fma_f32 v[22:23], v[108:109], v[172:173], v[22:23]
	v_pk_fma_f32 v[22:23], v[110:111], v[174:175], v[22:23]
	ds_read_b128 v[160:163], v26 offset:28800
	ds_read_b128 v[164:167], v26 offset:28816
	ds_read_b128 v[168:171], v26 offset:28832
	ds_read_b128 v[172:175], v26 offset:28848
	s_waitcnt lgkmcnt(8)
	v_pk_fma_f32 v[24:25], v[96:97], v[0:1], v[24:25]
	v_pk_fma_f32 v[24:25], v[98:99], v[2:3], v[24:25]
	v_pk_fma_f32 v[24:25], v[100:101], v[4:5], v[24:25]
	v_pk_fma_f32 v[24:25], v[102:103], v[6:7], v[24:25]
	v_pk_fma_f32 v[24:25], v[104:105], v[56:57], v[24:25]
	v_pk_fma_f32 v[24:25], v[106:107], v[58:59], v[24:25]
	v_pk_fma_f32 v[24:25], v[108:109], v[60:61], v[24:25]
	v_pk_fma_f32 v[24:25], v[110:111], v[62:63], v[24:25]
	ds_read_b128 v[0:3], v26 offset:32896
	ds_read_b128 v[4:7], v26 offset:32912
	ds_read_b128 v[56:59], v26 offset:32928
	ds_read_b128 v[60:63], v26 offset:32944
	s_waitcnt lgkmcnt(8)
	v_pk_fma_f32 v[30:31], v[96:97], v[40:41], v[30:31]
	v_pk_fma_f32 v[30:31], v[98:99], v[42:43], v[30:31]
	v_pk_fma_f32 v[30:31], v[100:101], v[44:45], v[30:31]
	v_pk_fma_f32 v[30:31], v[102:103], v[46:47], v[30:31]
	v_pk_fma_f32 v[30:31], v[104:105], v[48:49], v[30:31]
	v_pk_fma_f32 v[30:31], v[106:107], v[50:51], v[30:31]
	v_pk_fma_f32 v[30:31], v[108:109], v[52:53], v[30:31]
	v_pk_fma_f32 v[30:31], v[110:111], v[54:55], v[30:31]
	ds_read_b128 v[40:43], v26 offset:192
	ds_read_b128 v[44:47], v26 offset:208
	ds_read_b128 v[48:51], v26 offset:224
	ds_read_b128 v[52:55], v26 offset:240
	s_waitcnt lgkmcnt(8)
	v_pk_fma_f32 v[34:35], v[96:97], v[160:161], v[34:35]
	v_pk_fma_f32 v[34:35], v[98:99], v[162:163], v[34:35]
	v_pk_fma_f32 v[34:35], v[100:101], v[164:165], v[34:35]
	v_pk_fma_f32 v[34:35], v[102:103], v[166:167], v[34:35]
	v_pk_fma_f32 v[34:35], v[104:105], v[168:169], v[34:35]
	v_pk_fma_f32 v[34:35], v[106:107], v[170:171], v[34:35]
	v_pk_fma_f32 v[34:35], v[108:109], v[172:173], v[34:35]
	v_pk_fma_f32 v[34:35], v[110:111], v[174:175], v[34:35]
	ds_read_b128 v[160:163], v26 offset:4288
	ds_read_b128 v[164:167], v26 offset:4304
	ds_read_b128 v[168:171], v26 offset:4320
	ds_read_b128 v[172:175], v26 offset:4336
	s_waitcnt lgkmcnt(8)
	v_pk_fma_f32 v[38:39], v[96:97], v[0:1], v[38:39]
	v_pk_fma_f32 v[38:39], v[98:99], v[2:3], v[38:39]
	v_pk_fma_f32 v[38:39], v[100:101], v[4:5], v[38:39]
	v_pk_fma_f32 v[38:39], v[102:103], v[6:7], v[38:39]
	v_pk_fma_f32 v[38:39], v[104:105], v[56:57], v[38:39]
	v_pk_fma_f32 v[38:39], v[106:107], v[58:59], v[38:39]
	v_pk_fma_f32 v[38:39], v[108:109], v[60:61], v[38:39]
	v_pk_fma_f32 v[38:39], v[110:111], v[62:63], v[38:39]
	ds_read_b128 v[0:3], v26 offset:8384
	ds_read_b128 v[4:7], v26 offset:8400
	ds_read_b128 v[56:59], v26 offset:8416
	ds_read_b128 v[60:63], v26 offset:8432
	s_waitcnt vmcnt(32) lgkmcnt(8)
	v_pk_fma_f32 v[14:15], v[112:113], v[40:41], v[14:15]
	v_pk_fma_f32 v[14:15], v[114:115], v[42:43], v[14:15]
	v_pk_fma_f32 v[14:15], v[116:117], v[44:45], v[14:15]
	v_pk_fma_f32 v[14:15], v[118:119], v[46:47], v[14:15]
	v_pk_fma_f32 v[14:15], v[120:121], v[48:49], v[14:15]
	v_pk_fma_f32 v[14:15], v[122:123], v[50:51], v[14:15]
	v_pk_fma_f32 v[14:15], v[124:125], v[52:53], v[14:15]
	v_pk_fma_f32 v[14:15], v[126:127], v[54:55], v[14:15]
	global_load_dword v96, v27, s[98:99] nt
	s_add_u32 s98, s98, 0x9000
	s_addc_u32 s99, s99, 0
	global_load_dword v97, v27, s[98:99] nt
	s_add_u32 s98, s98, 0x9000
	s_addc_u32 s99, s99, 0
	global_load_dword v98, v27, s[98:99] nt
	s_add_u32 s98, s98, 0x9000
	s_addc_u32 s99, s99, 0
	global_load_dword v99, v27, s[98:99] nt
	s_add_u32 s98, s98, 0x9000
	s_addc_u32 s99, s99, 0
	global_load_dword v100, v27, s[98:99] nt
	s_add_u32 s98, s98, 0x9000
	s_addc_u32 s99, s99, 0
	global_load_dword v101, v27, s[98:99] nt
	s_add_u32 s98, s98, 0x9000
	s_addc_u32 s99, s99, 0
	global_load_dword v102, v27, s[98:99] nt
	s_add_u32 s98, s98, 0x9000
	s_addc_u32 s99, s99, 0
	global_load_dword v103, v27, s[98:99] nt
	s_add_u32 s98, s98, 0x9000
	s_addc_u32 s99, s99, 0
	global_load_dword v104, v27, s[98:99] nt
	s_add_u32 s98, s98, 0x9000
	s_addc_u32 s99, s99, 0
	global_load_dword v105, v27, s[98:99] nt
	s_add_u32 s98, s98, 0x9000
	s_addc_u32 s99, s99, 0
	global_load_dword v106, v27, s[98:99] nt
	s_add_u32 s98, s98, 0x9000
	s_addc_u32 s99, s99, 0
	global_load_dword v107, v27, s[98:99] nt
	s_add_u32 s98, s98, 0x9000
	s_addc_u32 s99, s99, 0
	global_load_dword v108, v27, s[98:99] nt
	s_add_u32 s98, s98, 0x9000
	s_addc_u32 s99, s99, 0
	global_load_dword v109, v27, s[98:99] nt
	s_add_u32 s98, s98, 0x9000
	s_addc_u32 s99, s99, 0
	global_load_dword v110, v27, s[98:99] nt
	s_add_u32 s98, s98, 0x9000
	s_addc_u32 s99, s99, 0
	global_load_dword v111, v27, s[98:99] nt
	s_add_u32 s98, s98, 0x9000
	s_addc_u32 s99, s99, 0
	ds_read_b128 v[40:43], v26 offset:12480
	ds_read_b128 v[44:47], v26 offset:12496
	ds_read_b128 v[48:51], v26 offset:12512
	ds_read_b128 v[52:55], v26 offset:12528
	s_waitcnt lgkmcnt(8)
	v_pk_fma_f32 v[16:17], v[112:113], v[160:161], v[16:17]
	v_pk_fma_f32 v[16:17], v[114:115], v[162:163], v[16:17]
	v_pk_fma_f32 v[16:17], v[116:117], v[164:165], v[16:17]
	v_pk_fma_f32 v[16:17], v[118:119], v[166:167], v[16:17]
	v_pk_fma_f32 v[16:17], v[120:121], v[168:169], v[16:17]
	v_pk_fma_f32 v[16:17], v[122:123], v[170:171], v[16:17]
	v_pk_fma_f32 v[16:17], v[124:125], v[172:173], v[16:17]
	v_pk_fma_f32 v[16:17], v[126:127], v[174:175], v[16:17]
	ds_read_b128 v[160:163], v26 offset:16576
	ds_read_b128 v[164:167], v26 offset:16592
	ds_read_b128 v[168:171], v26 offset:16608
	ds_read_b128 v[172:175], v26 offset:16624
	s_waitcnt lgkmcnt(8)
	v_pk_fma_f32 v[18:19], v[112:113], v[0:1], v[18:19]
	v_pk_fma_f32 v[18:19], v[114:115], v[2:3], v[18:19]
	v_pk_fma_f32 v[18:19], v[116:117], v[4:5], v[18:19]
	v_pk_fma_f32 v[18:19], v[118:119], v[6:7], v[18:19]
	v_pk_fma_f32 v[18:19], v[120:121], v[56:57], v[18:19]
	v_pk_fma_f32 v[18:19], v[122:123], v[58:59], v[18:19]
	v_pk_fma_f32 v[18:19], v[124:125], v[60:61], v[18:19]
	v_pk_fma_f32 v[18:19], v[126:127], v[62:63], v[18:19]
	ds_read_b128 v[0:3], v26 offset:20672
	ds_read_b128 v[4:7], v26 offset:20688
	ds_read_b128 v[56:59], v26 offset:20704
	ds_read_b128 v[60:63], v26 offset:20720
	s_waitcnt lgkmcnt(8)
	v_pk_fma_f32 v[20:21], v[112:113], v[40:41], v[20:21]
	v_pk_fma_f32 v[20:21], v[114:115], v[42:43], v[20:21]
	v_pk_fma_f32 v[20:21], v[116:117], v[44:45], v[20:21]
	v_pk_fma_f32 v[20:21], v[118:119], v[46:47], v[20:21]
	v_pk_fma_f32 v[20:21], v[120:121], v[48:49], v[20:21]
	v_pk_fma_f32 v[20:21], v[122:123], v[50:51], v[20:21]
	v_pk_fma_f32 v[20:21], v[124:125], v[52:53], v[20:21]
	v_pk_fma_f32 v[20:21], v[126:127], v[54:55], v[20:21]
	ds_read_b128 v[40:43], v26 offset:24768
	ds_read_b128 v[44:47], v26 offset:24784
	ds_read_b128 v[48:51], v26 offset:24800
	ds_read_b128 v[52:55], v26 offset:24816
	s_waitcnt lgkmcnt(8)
	v_pk_fma_f32 v[22:23], v[112:113], v[160:161], v[22:23]
	v_pk_fma_f32 v[22:23], v[114:115], v[162:163], v[22:23]
	v_pk_fma_f32 v[22:23], v[116:117], v[164:165], v[22:23]
	v_pk_fma_f32 v[22:23], v[118:119], v[166:167], v[22:23]
	v_pk_fma_f32 v[22:23], v[120:121], v[168:169], v[22:23]
	v_pk_fma_f32 v[22:23], v[122:123], v[170:171], v[22:23]
	v_pk_fma_f32 v[22:23], v[124:125], v[172:173], v[22:23]
	v_pk_fma_f32 v[22:23], v[126:127], v[174:175], v[22:23]
	ds_read_b128 v[160:163], v26 offset:28864
	ds_read_b128 v[164:167], v26 offset:28880
	ds_read_b128 v[168:171], v26 offset:28896
	ds_read_b128 v[172:175], v26 offset:28912
	s_waitcnt lgkmcnt(8)
	v_pk_fma_f32 v[24:25], v[112:113], v[0:1], v[24:25]
	v_pk_fma_f32 v[24:25], v[114:115], v[2:3], v[24:25]
	v_pk_fma_f32 v[24:25], v[116:117], v[4:5], v[24:25]
	v_pk_fma_f32 v[24:25], v[118:119], v[6:7], v[24:25]
	v_pk_fma_f32 v[24:25], v[120:121], v[56:57], v[24:25]
	v_pk_fma_f32 v[24:25], v[122:123], v[58:59], v[24:25]
	v_pk_fma_f32 v[24:25], v[124:125], v[60:61], v[24:25]
	v_pk_fma_f32 v[24:25], v[126:127], v[62:63], v[24:25]
	ds_read_b128 v[0:3], v26 offset:32960
	ds_read_b128 v[4:7], v26 offset:32976
	ds_read_b128 v[56:59], v26 offset:32992
	ds_read_b128 v[60:63], v26 offset:33008
	s_waitcnt lgkmcnt(8)
	v_pk_fma_f32 v[30:31], v[112:113], v[40:41], v[30:31]
	v_pk_fma_f32 v[30:31], v[114:115], v[42:43], v[30:31]
	v_pk_fma_f32 v[30:31], v[116:117], v[44:45], v[30:31]
	v_pk_fma_f32 v[30:31], v[118:119], v[46:47], v[30:31]
	v_pk_fma_f32 v[30:31], v[120:121], v[48:49], v[30:31]
	v_pk_fma_f32 v[30:31], v[122:123], v[50:51], v[30:31]
	v_pk_fma_f32 v[30:31], v[124:125], v[52:53], v[30:31]
	v_pk_fma_f32 v[30:31], v[126:127], v[54:55], v[30:31]
	ds_read_b128 v[40:43], v26 offset:256
	ds_read_b128 v[44:47], v26 offset:272
	ds_read_b128 v[48:51], v26 offset:288
	ds_read_b128 v[52:55], v26 offset:304
	s_waitcnt lgkmcnt(8)
	v_pk_fma_f32 v[34:35], v[112:113], v[160:161], v[34:35]
	v_pk_fma_f32 v[34:35], v[114:115], v[162:163], v[34:35]
	v_pk_fma_f32 v[34:35], v[116:117], v[164:165], v[34:35]
	v_pk_fma_f32 v[34:35], v[118:119], v[166:167], v[34:35]
	v_pk_fma_f32 v[34:35], v[120:121], v[168:169], v[34:35]
	v_pk_fma_f32 v[34:35], v[122:123], v[170:171], v[34:35]
	v_pk_fma_f32 v[34:35], v[124:125], v[172:173], v[34:35]
	v_pk_fma_f32 v[34:35], v[126:127], v[174:175], v[34:35]
	ds_read_b128 v[160:163], v26 offset:4352
	ds_read_b128 v[164:167], v26 offset:4368
	ds_read_b128 v[168:171], v26 offset:4384
	ds_read_b128 v[172:175], v26 offset:4400
	s_waitcnt lgkmcnt(8)
	v_pk_fma_f32 v[38:39], v[112:113], v[0:1], v[38:39]
	v_pk_fma_f32 v[38:39], v[114:115], v[2:3], v[38:39]
	v_pk_fma_f32 v[38:39], v[116:117], v[4:5], v[38:39]
	v_pk_fma_f32 v[38:39], v[118:119], v[6:7], v[38:39]
	v_pk_fma_f32 v[38:39], v[120:121], v[56:57], v[38:39]
	v_pk_fma_f32 v[38:39], v[122:123], v[58:59], v[38:39]
	v_pk_fma_f32 v[38:39], v[124:125], v[60:61], v[38:39]
	v_pk_fma_f32 v[38:39], v[126:127], v[62:63], v[38:39]
	ds_read_b128 v[0:3], v26 offset:8448
	ds_read_b128 v[4:7], v26 offset:8464
	ds_read_b128 v[56:59], v26 offset:8480
	ds_read_b128 v[60:63], v26 offset:8496
	s_waitcnt vmcnt(32) lgkmcnt(8)
	v_pk_fma_f32 v[14:15], v[64:65], v[40:41], v[14:15]
	v_pk_fma_f32 v[14:15], v[66:67], v[42:43], v[14:15]
	v_pk_fma_f32 v[14:15], v[68:69], v[44:45], v[14:15]
	v_pk_fma_f32 v[14:15], v[70:71], v[46:47], v[14:15]
	v_pk_fma_f32 v[14:15], v[72:73], v[48:49], v[14:15]
	v_pk_fma_f32 v[14:15], v[74:75], v[50:51], v[14:15]
	v_pk_fma_f32 v[14:15], v[76:77], v[52:53], v[14:15]
	v_pk_fma_f32 v[14:15], v[78:79], v[54:55], v[14:15]
	global_load_dword v112, v27, s[98:99] nt
	s_add_u32 s98, s98, 0x9000
	s_addc_u32 s99, s99, 0
	global_load_dword v113, v27, s[98:99] nt
	s_add_u32 s98, s98, 0x9000
	s_addc_u32 s99, s99, 0
	global_load_dword v114, v27, s[98:99] nt
	s_add_u32 s98, s98, 0x9000
	s_addc_u32 s99, s99, 0
	global_load_dword v115, v27, s[98:99] nt
	s_add_u32 s98, s98, 0x9000
	s_addc_u32 s99, s99, 0
	global_load_dword v116, v27, s[98:99] nt
	s_add_u32 s98, s98, 0x9000
	s_addc_u32 s99, s99, 0
	global_load_dword v117, v27, s[98:99] nt
	s_add_u32 s98, s98, 0x9000
	s_addc_u32 s99, s99, 0
	global_load_dword v118, v27, s[98:99] nt
	s_add_u32 s98, s98, 0x9000
	s_addc_u32 s99, s99, 0
	global_load_dword v119, v27, s[98:99] nt
	s_add_u32 s98, s98, 0x9000
	s_addc_u32 s99, s99, 0
	global_load_dword v120, v27, s[98:99] nt
	s_add_u32 s98, s98, 0x9000
	s_addc_u32 s99, s99, 0
	global_load_dword v121, v27, s[98:99] nt
	s_add_u32 s98, s98, 0x9000
	s_addc_u32 s99, s99, 0
	global_load_dword v122, v27, s[98:99] nt
	s_add_u32 s98, s98, 0x9000
	s_addc_u32 s99, s99, 0
	global_load_dword v123, v27, s[98:99] nt
	s_add_u32 s98, s98, 0x9000
	s_addc_u32 s99, s99, 0
	global_load_dword v124, v27, s[98:99] nt
	s_add_u32 s98, s98, 0x9000
	s_addc_u32 s99, s99, 0
	global_load_dword v125, v27, s[98:99] nt
	s_add_u32 s98, s98, 0x9000
	s_addc_u32 s99, s99, 0
	global_load_dword v126, v27, s[98:99] nt
	s_add_u32 s98, s98, 0x9000
	s_addc_u32 s99, s99, 0
	global_load_dword v127, v27, s[98:99] nt
	s_add_u32 s98, s98, 0x9000
	s_addc_u32 s99, s99, 0
	ds_read_b128 v[40:43], v26 offset:12544
	ds_read_b128 v[44:47], v26 offset:12560
	ds_read_b128 v[48:51], v26 offset:12576
	ds_read_b128 v[52:55], v26 offset:12592
	s_waitcnt lgkmcnt(8)
	v_pk_fma_f32 v[16:17], v[64:65], v[160:161], v[16:17]
	v_pk_fma_f32 v[16:17], v[66:67], v[162:163], v[16:17]
	v_pk_fma_f32 v[16:17], v[68:69], v[164:165], v[16:17]
	v_pk_fma_f32 v[16:17], v[70:71], v[166:167], v[16:17]
	v_pk_fma_f32 v[16:17], v[72:73], v[168:169], v[16:17]
	v_pk_fma_f32 v[16:17], v[74:75], v[170:171], v[16:17]
	v_pk_fma_f32 v[16:17], v[76:77], v[172:173], v[16:17]
	v_pk_fma_f32 v[16:17], v[78:79], v[174:175], v[16:17]
	ds_read_b128 v[160:163], v26 offset:16640
	ds_read_b128 v[164:167], v26 offset:16656
	ds_read_b128 v[168:171], v26 offset:16672
	ds_read_b128 v[172:175], v26 offset:16688
	s_waitcnt lgkmcnt(8)
	v_pk_fma_f32 v[18:19], v[64:65], v[0:1], v[18:19]
	v_pk_fma_f32 v[18:19], v[66:67], v[2:3], v[18:19]
	v_pk_fma_f32 v[18:19], v[68:69], v[4:5], v[18:19]
	v_pk_fma_f32 v[18:19], v[70:71], v[6:7], v[18:19]
	v_pk_fma_f32 v[18:19], v[72:73], v[56:57], v[18:19]
	v_pk_fma_f32 v[18:19], v[74:75], v[58:59], v[18:19]
	v_pk_fma_f32 v[18:19], v[76:77], v[60:61], v[18:19]
	v_pk_fma_f32 v[18:19], v[78:79], v[62:63], v[18:19]
	ds_read_b128 v[0:3], v26 offset:20736
	ds_read_b128 v[4:7], v26 offset:20752
	ds_read_b128 v[56:59], v26 offset:20768
	ds_read_b128 v[60:63], v26 offset:20784
	s_waitcnt lgkmcnt(8)
	v_pk_fma_f32 v[20:21], v[64:65], v[40:41], v[20:21]
	v_pk_fma_f32 v[20:21], v[66:67], v[42:43], v[20:21]
	v_pk_fma_f32 v[20:21], v[68:69], v[44:45], v[20:21]
	v_pk_fma_f32 v[20:21], v[70:71], v[46:47], v[20:21]
	v_pk_fma_f32 v[20:21], v[72:73], v[48:49], v[20:21]
	v_pk_fma_f32 v[20:21], v[74:75], v[50:51], v[20:21]
	v_pk_fma_f32 v[20:21], v[76:77], v[52:53], v[20:21]
	v_pk_fma_f32 v[20:21], v[78:79], v[54:55], v[20:21]
	ds_read_b128 v[40:43], v26 offset:24832
	ds_read_b128 v[44:47], v26 offset:24848
	ds_read_b128 v[48:51], v26 offset:24864
	ds_read_b128 v[52:55], v26 offset:24880
	s_waitcnt lgkmcnt(8)
	v_pk_fma_f32 v[22:23], v[64:65], v[160:161], v[22:23]
	v_pk_fma_f32 v[22:23], v[66:67], v[162:163], v[22:23]
	v_pk_fma_f32 v[22:23], v[68:69], v[164:165], v[22:23]
	v_pk_fma_f32 v[22:23], v[70:71], v[166:167], v[22:23]
	v_pk_fma_f32 v[22:23], v[72:73], v[168:169], v[22:23]
	v_pk_fma_f32 v[22:23], v[74:75], v[170:171], v[22:23]
	v_pk_fma_f32 v[22:23], v[76:77], v[172:173], v[22:23]
	v_pk_fma_f32 v[22:23], v[78:79], v[174:175], v[22:23]
	ds_read_b128 v[160:163], v26 offset:28928
	ds_read_b128 v[164:167], v26 offset:28944
	ds_read_b128 v[168:171], v26 offset:28960
	ds_read_b128 v[172:175], v26 offset:28976
	s_waitcnt lgkmcnt(8)
	v_pk_fma_f32 v[24:25], v[64:65], v[0:1], v[24:25]
	v_pk_fma_f32 v[24:25], v[66:67], v[2:3], v[24:25]
	v_pk_fma_f32 v[24:25], v[68:69], v[4:5], v[24:25]
	v_pk_fma_f32 v[24:25], v[70:71], v[6:7], v[24:25]
	v_pk_fma_f32 v[24:25], v[72:73], v[56:57], v[24:25]
	v_pk_fma_f32 v[24:25], v[74:75], v[58:59], v[24:25]
	v_pk_fma_f32 v[24:25], v[76:77], v[60:61], v[24:25]
	v_pk_fma_f32 v[24:25], v[78:79], v[62:63], v[24:25]
	ds_read_b128 v[0:3], v26 offset:33024
	ds_read_b128 v[4:7], v26 offset:33040
	ds_read_b128 v[56:59], v26 offset:33056
	ds_read_b128 v[60:63], v26 offset:33072
	s_waitcnt lgkmcnt(8)
	v_pk_fma_f32 v[30:31], v[64:65], v[40:41], v[30:31]
	v_pk_fma_f32 v[30:31], v[66:67], v[42:43], v[30:31]
	v_pk_fma_f32 v[30:31], v[68:69], v[44:45], v[30:31]
	v_pk_fma_f32 v[30:31], v[70:71], v[46:47], v[30:31]
	v_pk_fma_f32 v[30:31], v[72:73], v[48:49], v[30:31]
	v_pk_fma_f32 v[30:31], v[74:75], v[50:51], v[30:31]
	v_pk_fma_f32 v[30:31], v[76:77], v[52:53], v[30:31]
	v_pk_fma_f32 v[30:31], v[78:79], v[54:55], v[30:31]
	ds_read_b128 v[40:43], v26 offset:320
	ds_read_b128 v[44:47], v26 offset:336
	ds_read_b128 v[48:51], v26 offset:352
	ds_read_b128 v[52:55], v26 offset:368
	s_waitcnt lgkmcnt(8)
	v_pk_fma_f32 v[34:35], v[64:65], v[160:161], v[34:35]
	v_pk_fma_f32 v[34:35], v[66:67], v[162:163], v[34:35]
	v_pk_fma_f32 v[34:35], v[68:69], v[164:165], v[34:35]
	v_pk_fma_f32 v[34:35], v[70:71], v[166:167], v[34:35]
	v_pk_fma_f32 v[34:35], v[72:73], v[168:169], v[34:35]
	v_pk_fma_f32 v[34:35], v[74:75], v[170:171], v[34:35]
	v_pk_fma_f32 v[34:35], v[76:77], v[172:173], v[34:35]
	v_pk_fma_f32 v[34:35], v[78:79], v[174:175], v[34:35]
	ds_read_b128 v[160:163], v26 offset:4416
	ds_read_b128 v[164:167], v26 offset:4432
	ds_read_b128 v[168:171], v26 offset:4448
	ds_read_b128 v[172:175], v26 offset:4464
	s_waitcnt lgkmcnt(8)
	v_pk_fma_f32 v[38:39], v[64:65], v[0:1], v[38:39]
	v_pk_fma_f32 v[38:39], v[66:67], v[2:3], v[38:39]
	v_pk_fma_f32 v[38:39], v[68:69], v[4:5], v[38:39]
	v_pk_fma_f32 v[38:39], v[70:71], v[6:7], v[38:39]
	v_pk_fma_f32 v[38:39], v[72:73], v[56:57], v[38:39]
	v_pk_fma_f32 v[38:39], v[74:75], v[58:59], v[38:39]
	v_pk_fma_f32 v[38:39], v[76:77], v[60:61], v[38:39]
	v_pk_fma_f32 v[38:39], v[78:79], v[62:63], v[38:39]
	ds_read_b128 v[0:3], v26 offset:8512
	ds_read_b128 v[4:7], v26 offset:8528
	ds_read_b128 v[56:59], v26 offset:8544
	ds_read_b128 v[60:63], v26 offset:8560
	s_waitcnt vmcnt(32) lgkmcnt(8)
	v_pk_fma_f32 v[14:15], v[80:81], v[40:41], v[14:15]
	v_pk_fma_f32 v[14:15], v[82:83], v[42:43], v[14:15]
	v_pk_fma_f32 v[14:15], v[84:85], v[44:45], v[14:15]
	v_pk_fma_f32 v[14:15], v[86:87], v[46:47], v[14:15]
	v_pk_fma_f32 v[14:15], v[88:89], v[48:49], v[14:15]
	v_pk_fma_f32 v[14:15], v[90:91], v[50:51], v[14:15]
	v_pk_fma_f32 v[14:15], v[92:93], v[52:53], v[14:15]
	v_pk_fma_f32 v[14:15], v[94:95], v[54:55], v[14:15]
	ds_read_b128 v[40:43], v26 offset:12608
	ds_read_b128 v[44:47], v26 offset:12624
	ds_read_b128 v[48:51], v26 offset:12640
	ds_read_b128 v[52:55], v26 offset:12656
	s_waitcnt lgkmcnt(8)
	v_pk_fma_f32 v[16:17], v[80:81], v[160:161], v[16:17]
	v_pk_fma_f32 v[16:17], v[82:83], v[162:163], v[16:17]
	v_pk_fma_f32 v[16:17], v[84:85], v[164:165], v[16:17]
	v_pk_fma_f32 v[16:17], v[86:87], v[166:167], v[16:17]
	v_pk_fma_f32 v[16:17], v[88:89], v[168:169], v[16:17]
	v_pk_fma_f32 v[16:17], v[90:91], v[170:171], v[16:17]
	v_pk_fma_f32 v[16:17], v[92:93], v[172:173], v[16:17]
	v_pk_fma_f32 v[16:17], v[94:95], v[174:175], v[16:17]
	ds_read_b128 v[160:163], v26 offset:16704
	ds_read_b128 v[164:167], v26 offset:16720
	ds_read_b128 v[168:171], v26 offset:16736
	ds_read_b128 v[172:175], v26 offset:16752
	s_waitcnt lgkmcnt(8)
	v_pk_fma_f32 v[18:19], v[80:81], v[0:1], v[18:19]
	v_pk_fma_f32 v[18:19], v[82:83], v[2:3], v[18:19]
	v_pk_fma_f32 v[18:19], v[84:85], v[4:5], v[18:19]
	v_pk_fma_f32 v[18:19], v[86:87], v[6:7], v[18:19]
	v_pk_fma_f32 v[18:19], v[88:89], v[56:57], v[18:19]
	v_pk_fma_f32 v[18:19], v[90:91], v[58:59], v[18:19]
	v_pk_fma_f32 v[18:19], v[92:93], v[60:61], v[18:19]
	v_pk_fma_f32 v[18:19], v[94:95], v[62:63], v[18:19]
	ds_read_b128 v[0:3], v26 offset:20800
	ds_read_b128 v[4:7], v26 offset:20816
	ds_read_b128 v[56:59], v26 offset:20832
	ds_read_b128 v[60:63], v26 offset:20848
	s_waitcnt lgkmcnt(8)
	v_pk_fma_f32 v[20:21], v[80:81], v[40:41], v[20:21]
	v_pk_fma_f32 v[20:21], v[82:83], v[42:43], v[20:21]
	v_pk_fma_f32 v[20:21], v[84:85], v[44:45], v[20:21]
	v_pk_fma_f32 v[20:21], v[86:87], v[46:47], v[20:21]
	v_pk_fma_f32 v[20:21], v[88:89], v[48:49], v[20:21]
	v_pk_fma_f32 v[20:21], v[90:91], v[50:51], v[20:21]
	v_pk_fma_f32 v[20:21], v[92:93], v[52:53], v[20:21]
	v_pk_fma_f32 v[20:21], v[94:95], v[54:55], v[20:21]
	ds_read_b128 v[40:43], v26 offset:24896
	ds_read_b128 v[44:47], v26 offset:24912
	ds_read_b128 v[48:51], v26 offset:24928
	ds_read_b128 v[52:55], v26 offset:24944
	s_waitcnt lgkmcnt(8)
	v_pk_fma_f32 v[22:23], v[80:81], v[160:161], v[22:23]
	v_pk_fma_f32 v[22:23], v[82:83], v[162:163], v[22:23]
	v_pk_fma_f32 v[22:23], v[84:85], v[164:165], v[22:23]
	v_pk_fma_f32 v[22:23], v[86:87], v[166:167], v[22:23]
	v_pk_fma_f32 v[22:23], v[88:89], v[168:169], v[22:23]
	v_pk_fma_f32 v[22:23], v[90:91], v[170:171], v[22:23]
	v_pk_fma_f32 v[22:23], v[92:93], v[172:173], v[22:23]
	v_pk_fma_f32 v[22:23], v[94:95], v[174:175], v[22:23]
	ds_read_b128 v[160:163], v26 offset:28992
	ds_read_b128 v[164:167], v26 offset:29008
	ds_read_b128 v[168:171], v26 offset:29024
	ds_read_b128 v[172:175], v26 offset:29040
	s_waitcnt lgkmcnt(8)
	v_pk_fma_f32 v[24:25], v[80:81], v[0:1], v[24:25]
	v_pk_fma_f32 v[24:25], v[82:83], v[2:3], v[24:25]
	v_pk_fma_f32 v[24:25], v[84:85], v[4:5], v[24:25]
	v_pk_fma_f32 v[24:25], v[86:87], v[6:7], v[24:25]
	v_pk_fma_f32 v[24:25], v[88:89], v[56:57], v[24:25]
	v_pk_fma_f32 v[24:25], v[90:91], v[58:59], v[24:25]
	v_pk_fma_f32 v[24:25], v[92:93], v[60:61], v[24:25]
	v_pk_fma_f32 v[24:25], v[94:95], v[62:63], v[24:25]
	ds_read_b128 v[0:3], v26 offset:33088
	ds_read_b128 v[4:7], v26 offset:33104
	ds_read_b128 v[56:59], v26 offset:33120
	ds_read_b128 v[60:63], v26 offset:33136
	s_waitcnt lgkmcnt(8)
	v_pk_fma_f32 v[30:31], v[80:81], v[40:41], v[30:31]
	v_pk_fma_f32 v[30:31], v[82:83], v[42:43], v[30:31]
	v_pk_fma_f32 v[30:31], v[84:85], v[44:45], v[30:31]
	v_pk_fma_f32 v[30:31], v[86:87], v[46:47], v[30:31]
	v_pk_fma_f32 v[30:31], v[88:89], v[48:49], v[30:31]
	v_pk_fma_f32 v[30:31], v[90:91], v[50:51], v[30:31]
	v_pk_fma_f32 v[30:31], v[92:93], v[52:53], v[30:31]
	v_pk_fma_f32 v[30:31], v[94:95], v[54:55], v[30:31]
	ds_read_b128 v[40:43], v26 offset:384
	ds_read_b128 v[44:47], v26 offset:400
	ds_read_b128 v[48:51], v26 offset:416
	ds_read_b128 v[52:55], v26 offset:432
	s_waitcnt lgkmcnt(8)
	v_pk_fma_f32 v[34:35], v[80:81], v[160:161], v[34:35]
	v_pk_fma_f32 v[34:35], v[82:83], v[162:163], v[34:35]
	v_pk_fma_f32 v[34:35], v[84:85], v[164:165], v[34:35]
	v_pk_fma_f32 v[34:35], v[86:87], v[166:167], v[34:35]
	v_pk_fma_f32 v[34:35], v[88:89], v[168:169], v[34:35]
	v_pk_fma_f32 v[34:35], v[90:91], v[170:171], v[34:35]
	v_pk_fma_f32 v[34:35], v[92:93], v[172:173], v[34:35]
	v_pk_fma_f32 v[34:35], v[94:95], v[174:175], v[34:35]
	ds_read_b128 v[160:163], v26 offset:4480
	ds_read_b128 v[164:167], v26 offset:4496
	ds_read_b128 v[168:171], v26 offset:4512
	ds_read_b128 v[172:175], v26 offset:4528
	s_waitcnt lgkmcnt(8)
	v_pk_fma_f32 v[38:39], v[80:81], v[0:1], v[38:39]
	v_pk_fma_f32 v[38:39], v[82:83], v[2:3], v[38:39]
	v_pk_fma_f32 v[38:39], v[84:85], v[4:5], v[38:39]
	v_pk_fma_f32 v[38:39], v[86:87], v[6:7], v[38:39]
	v_pk_fma_f32 v[38:39], v[88:89], v[56:57], v[38:39]
	v_pk_fma_f32 v[38:39], v[90:91], v[58:59], v[38:39]
	v_pk_fma_f32 v[38:39], v[92:93], v[60:61], v[38:39]
	v_pk_fma_f32 v[38:39], v[94:95], v[62:63], v[38:39]
	ds_read_b128 v[0:3], v26 offset:8576
	ds_read_b128 v[4:7], v26 offset:8592
	ds_read_b128 v[56:59], v26 offset:8608
	ds_read_b128 v[60:63], v26 offset:8624
	s_waitcnt vmcnt(16) lgkmcnt(8)
	v_pk_fma_f32 v[14:15], v[96:97], v[40:41], v[14:15]
	v_pk_fma_f32 v[14:15], v[98:99], v[42:43], v[14:15]
	v_pk_fma_f32 v[14:15], v[100:101], v[44:45], v[14:15]
	v_pk_fma_f32 v[14:15], v[102:103], v[46:47], v[14:15]
	v_pk_fma_f32 v[14:15], v[104:105], v[48:49], v[14:15]
	v_pk_fma_f32 v[14:15], v[106:107], v[50:51], v[14:15]
	v_pk_fma_f32 v[14:15], v[108:109], v[52:53], v[14:15]
	v_pk_fma_f32 v[14:15], v[110:111], v[54:55], v[14:15]
	ds_read_b128 v[40:43], v26 offset:12672
	ds_read_b128 v[44:47], v26 offset:12688
	ds_read_b128 v[48:51], v26 offset:12704
	ds_read_b128 v[52:55], v26 offset:12720
	s_waitcnt lgkmcnt(8)
	v_pk_fma_f32 v[16:17], v[96:97], v[160:161], v[16:17]
	v_pk_fma_f32 v[16:17], v[98:99], v[162:163], v[16:17]
	v_pk_fma_f32 v[16:17], v[100:101], v[164:165], v[16:17]
	v_pk_fma_f32 v[16:17], v[102:103], v[166:167], v[16:17]
	v_pk_fma_f32 v[16:17], v[104:105], v[168:169], v[16:17]
	v_pk_fma_f32 v[16:17], v[106:107], v[170:171], v[16:17]
	v_pk_fma_f32 v[16:17], v[108:109], v[172:173], v[16:17]
	v_pk_fma_f32 v[16:17], v[110:111], v[174:175], v[16:17]
	ds_read_b128 v[160:163], v26 offset:16768
	ds_read_b128 v[164:167], v26 offset:16784
	ds_read_b128 v[168:171], v26 offset:16800
	ds_read_b128 v[172:175], v26 offset:16816
	s_waitcnt lgkmcnt(8)
	v_pk_fma_f32 v[18:19], v[96:97], v[0:1], v[18:19]
	v_pk_fma_f32 v[18:19], v[98:99], v[2:3], v[18:19]
	v_pk_fma_f32 v[18:19], v[100:101], v[4:5], v[18:19]
	v_pk_fma_f32 v[18:19], v[102:103], v[6:7], v[18:19]
	v_pk_fma_f32 v[18:19], v[104:105], v[56:57], v[18:19]
	v_pk_fma_f32 v[18:19], v[106:107], v[58:59], v[18:19]
	v_pk_fma_f32 v[18:19], v[108:109], v[60:61], v[18:19]
	v_pk_fma_f32 v[18:19], v[110:111], v[62:63], v[18:19]
	ds_read_b128 v[0:3], v26 offset:20864
	ds_read_b128 v[4:7], v26 offset:20880
	ds_read_b128 v[56:59], v26 offset:20896
	ds_read_b128 v[60:63], v26 offset:20912
	s_waitcnt lgkmcnt(8)
	v_pk_fma_f32 v[20:21], v[96:97], v[40:41], v[20:21]
	v_pk_fma_f32 v[20:21], v[98:99], v[42:43], v[20:21]
	v_pk_fma_f32 v[20:21], v[100:101], v[44:45], v[20:21]
	v_pk_fma_f32 v[20:21], v[102:103], v[46:47], v[20:21]
	v_pk_fma_f32 v[20:21], v[104:105], v[48:49], v[20:21]
	v_pk_fma_f32 v[20:21], v[106:107], v[50:51], v[20:21]
	v_pk_fma_f32 v[20:21], v[108:109], v[52:53], v[20:21]
	v_pk_fma_f32 v[20:21], v[110:111], v[54:55], v[20:21]
	ds_read_b128 v[40:43], v26 offset:24960
	ds_read_b128 v[44:47], v26 offset:24976
	ds_read_b128 v[48:51], v26 offset:24992
	ds_read_b128 v[52:55], v26 offset:25008
	s_waitcnt lgkmcnt(8)
	v_pk_fma_f32 v[22:23], v[96:97], v[160:161], v[22:23]
	v_pk_fma_f32 v[22:23], v[98:99], v[162:163], v[22:23]
	v_pk_fma_f32 v[22:23], v[100:101], v[164:165], v[22:23]
	v_pk_fma_f32 v[22:23], v[102:103], v[166:167], v[22:23]
	v_pk_fma_f32 v[22:23], v[104:105], v[168:169], v[22:23]
	v_pk_fma_f32 v[22:23], v[106:107], v[170:171], v[22:23]
	v_pk_fma_f32 v[22:23], v[108:109], v[172:173], v[22:23]
	v_pk_fma_f32 v[22:23], v[110:111], v[174:175], v[22:23]
	ds_read_b128 v[160:163], v26 offset:29056
	ds_read_b128 v[164:167], v26 offset:29072
	ds_read_b128 v[168:171], v26 offset:29088
	ds_read_b128 v[172:175], v26 offset:29104
	s_waitcnt lgkmcnt(8)
	v_pk_fma_f32 v[24:25], v[96:97], v[0:1], v[24:25]
	v_pk_fma_f32 v[24:25], v[98:99], v[2:3], v[24:25]
	v_pk_fma_f32 v[24:25], v[100:101], v[4:5], v[24:25]
	v_pk_fma_f32 v[24:25], v[102:103], v[6:7], v[24:25]
	v_pk_fma_f32 v[24:25], v[104:105], v[56:57], v[24:25]
	v_pk_fma_f32 v[24:25], v[106:107], v[58:59], v[24:25]
	v_pk_fma_f32 v[24:25], v[108:109], v[60:61], v[24:25]
	v_pk_fma_f32 v[24:25], v[110:111], v[62:63], v[24:25]
	ds_read_b128 v[0:3], v26 offset:33152
	ds_read_b128 v[4:7], v26 offset:33168
	ds_read_b128 v[56:59], v26 offset:33184
	ds_read_b128 v[60:63], v26 offset:33200
	s_waitcnt lgkmcnt(8)
	v_pk_fma_f32 v[30:31], v[96:97], v[40:41], v[30:31]
	v_pk_fma_f32 v[30:31], v[98:99], v[42:43], v[30:31]
	v_pk_fma_f32 v[30:31], v[100:101], v[44:45], v[30:31]
	v_pk_fma_f32 v[30:31], v[102:103], v[46:47], v[30:31]
	v_pk_fma_f32 v[30:31], v[104:105], v[48:49], v[30:31]
	v_pk_fma_f32 v[30:31], v[106:107], v[50:51], v[30:31]
	v_pk_fma_f32 v[30:31], v[108:109], v[52:53], v[30:31]
	v_pk_fma_f32 v[30:31], v[110:111], v[54:55], v[30:31]
	ds_read_b128 v[40:43], v26 offset:448
	ds_read_b128 v[44:47], v26 offset:464
	ds_read_b128 v[48:51], v26 offset:480
	ds_read_b128 v[52:55], v26 offset:496
	s_waitcnt lgkmcnt(8)
	v_pk_fma_f32 v[34:35], v[96:97], v[160:161], v[34:35]
	v_pk_fma_f32 v[34:35], v[98:99], v[162:163], v[34:35]
	v_pk_fma_f32 v[34:35], v[100:101], v[164:165], v[34:35]
	v_pk_fma_f32 v[34:35], v[102:103], v[166:167], v[34:35]
	v_pk_fma_f32 v[34:35], v[104:105], v[168:169], v[34:35]
	v_pk_fma_f32 v[34:35], v[106:107], v[170:171], v[34:35]
	v_pk_fma_f32 v[34:35], v[108:109], v[172:173], v[34:35]
	v_pk_fma_f32 v[34:35], v[110:111], v[174:175], v[34:35]
	ds_read_b128 v[160:163], v26 offset:4544
	ds_read_b128 v[164:167], v26 offset:4560
	ds_read_b128 v[168:171], v26 offset:4576
	ds_read_b128 v[172:175], v26 offset:4592
	s_waitcnt lgkmcnt(8)
	v_pk_fma_f32 v[38:39], v[96:97], v[0:1], v[38:39]
	v_pk_fma_f32 v[38:39], v[98:99], v[2:3], v[38:39]
	v_pk_fma_f32 v[38:39], v[100:101], v[4:5], v[38:39]
	v_pk_fma_f32 v[38:39], v[102:103], v[6:7], v[38:39]
	v_pk_fma_f32 v[38:39], v[104:105], v[56:57], v[38:39]
	v_pk_fma_f32 v[38:39], v[106:107], v[58:59], v[38:39]
	v_pk_fma_f32 v[38:39], v[108:109], v[60:61], v[38:39]
	v_pk_fma_f32 v[38:39], v[110:111], v[62:63], v[38:39]
	ds_read_b128 v[0:3], v26 offset:8640
	ds_read_b128 v[4:7], v26 offset:8656
	ds_read_b128 v[56:59], v26 offset:8672
	ds_read_b128 v[60:63], v26 offset:8688
	s_waitcnt vmcnt(0) lgkmcnt(8)
	v_pk_fma_f32 v[14:15], v[112:113], v[40:41], v[14:15]
	v_pk_fma_f32 v[14:15], v[114:115], v[42:43], v[14:15]
	v_pk_fma_f32 v[14:15], v[116:117], v[44:45], v[14:15]
	v_pk_fma_f32 v[14:15], v[118:119], v[46:47], v[14:15]
	v_pk_fma_f32 v[14:15], v[120:121], v[48:49], v[14:15]
	v_pk_fma_f32 v[14:15], v[122:123], v[50:51], v[14:15]
	v_pk_fma_f32 v[14:15], v[124:125], v[52:53], v[14:15]
	v_pk_fma_f32 v[14:15], v[126:127], v[54:55], v[14:15]
	ds_read_b128 v[40:43], v26 offset:12736
	ds_read_b128 v[44:47], v26 offset:12752
	ds_read_b128 v[48:51], v26 offset:12768
	ds_read_b128 v[52:55], v26 offset:12784
	s_waitcnt lgkmcnt(8)
	v_pk_fma_f32 v[16:17], v[112:113], v[160:161], v[16:17]
	v_pk_fma_f32 v[16:17], v[114:115], v[162:163], v[16:17]
	v_pk_fma_f32 v[16:17], v[116:117], v[164:165], v[16:17]
	v_pk_fma_f32 v[16:17], v[118:119], v[166:167], v[16:17]
	v_pk_fma_f32 v[16:17], v[120:121], v[168:169], v[16:17]
	v_pk_fma_f32 v[16:17], v[122:123], v[170:171], v[16:17]
	v_pk_fma_f32 v[16:17], v[124:125], v[172:173], v[16:17]
	v_pk_fma_f32 v[16:17], v[126:127], v[174:175], v[16:17]
	ds_read_b128 v[160:163], v26 offset:16832
	ds_read_b128 v[164:167], v26 offset:16848
	ds_read_b128 v[168:171], v26 offset:16864
	ds_read_b128 v[172:175], v26 offset:16880
	s_waitcnt lgkmcnt(8)
	v_pk_fma_f32 v[18:19], v[112:113], v[0:1], v[18:19]
	v_pk_fma_f32 v[18:19], v[114:115], v[2:3], v[18:19]
	v_pk_fma_f32 v[18:19], v[116:117], v[4:5], v[18:19]
	v_pk_fma_f32 v[18:19], v[118:119], v[6:7], v[18:19]
	v_pk_fma_f32 v[18:19], v[120:121], v[56:57], v[18:19]
	v_pk_fma_f32 v[18:19], v[122:123], v[58:59], v[18:19]
	v_pk_fma_f32 v[18:19], v[124:125], v[60:61], v[18:19]
	v_pk_fma_f32 v[18:19], v[126:127], v[62:63], v[18:19]
	ds_read_b128 v[0:3], v26 offset:20928
	ds_read_b128 v[4:7], v26 offset:20944
	ds_read_b128 v[56:59], v26 offset:20960
	ds_read_b128 v[60:63], v26 offset:20976
	s_waitcnt lgkmcnt(8)
	v_pk_fma_f32 v[20:21], v[112:113], v[40:41], v[20:21]
	v_pk_fma_f32 v[20:21], v[114:115], v[42:43], v[20:21]
	v_pk_fma_f32 v[20:21], v[116:117], v[44:45], v[20:21]
	v_pk_fma_f32 v[20:21], v[118:119], v[46:47], v[20:21]
	v_pk_fma_f32 v[20:21], v[120:121], v[48:49], v[20:21]
	v_pk_fma_f32 v[20:21], v[122:123], v[50:51], v[20:21]
	v_pk_fma_f32 v[20:21], v[124:125], v[52:53], v[20:21]
	v_pk_fma_f32 v[20:21], v[126:127], v[54:55], v[20:21]
	ds_read_b128 v[40:43], v26 offset:25024
	ds_read_b128 v[44:47], v26 offset:25040
	ds_read_b128 v[48:51], v26 offset:25056
	ds_read_b128 v[52:55], v26 offset:25072
	s_waitcnt lgkmcnt(8)
	v_pk_fma_f32 v[22:23], v[112:113], v[160:161], v[22:23]
	v_pk_fma_f32 v[22:23], v[114:115], v[162:163], v[22:23]
	v_pk_fma_f32 v[22:23], v[116:117], v[164:165], v[22:23]
	v_pk_fma_f32 v[22:23], v[118:119], v[166:167], v[22:23]
	v_pk_fma_f32 v[22:23], v[120:121], v[168:169], v[22:23]
	v_pk_fma_f32 v[22:23], v[122:123], v[170:171], v[22:23]
	v_pk_fma_f32 v[22:23], v[124:125], v[172:173], v[22:23]
	v_pk_fma_f32 v[22:23], v[126:127], v[174:175], v[22:23]
	ds_read_b128 v[160:163], v26 offset:29120
	ds_read_b128 v[164:167], v26 offset:29136
	ds_read_b128 v[168:171], v26 offset:29152
	ds_read_b128 v[172:175], v26 offset:29168
	s_waitcnt lgkmcnt(8)
	v_pk_fma_f32 v[24:25], v[112:113], v[0:1], v[24:25]
	v_pk_fma_f32 v[24:25], v[114:115], v[2:3], v[24:25]
	v_pk_fma_f32 v[24:25], v[116:117], v[4:5], v[24:25]
	v_pk_fma_f32 v[24:25], v[118:119], v[6:7], v[24:25]
	v_pk_fma_f32 v[24:25], v[120:121], v[56:57], v[24:25]
	v_pk_fma_f32 v[24:25], v[122:123], v[58:59], v[24:25]
	v_pk_fma_f32 v[24:25], v[124:125], v[60:61], v[24:25]
	v_pk_fma_f32 v[24:25], v[126:127], v[62:63], v[24:25]
	ds_read_b128 v[0:3], v26 offset:33216
	ds_read_b128 v[4:7], v26 offset:33232
	ds_read_b128 v[56:59], v26 offset:33248
	ds_read_b128 v[60:63], v26 offset:33264
	s_waitcnt lgkmcnt(8)
	v_pk_fma_f32 v[30:31], v[112:113], v[40:41], v[30:31]
	v_pk_fma_f32 v[30:31], v[114:115], v[42:43], v[30:31]
	v_pk_fma_f32 v[30:31], v[116:117], v[44:45], v[30:31]
	v_pk_fma_f32 v[30:31], v[118:119], v[46:47], v[30:31]
	v_pk_fma_f32 v[30:31], v[120:121], v[48:49], v[30:31]
	v_pk_fma_f32 v[30:31], v[122:123], v[50:51], v[30:31]
	v_pk_fma_f32 v[30:31], v[124:125], v[52:53], v[30:31]
	v_pk_fma_f32 v[30:31], v[126:127], v[54:55], v[30:31]
	s_waitcnt lgkmcnt(4)
	v_pk_fma_f32 v[34:35], v[112:113], v[160:161], v[34:35]
	v_pk_fma_f32 v[34:35], v[114:115], v[162:163], v[34:35]
	v_pk_fma_f32 v[34:35], v[116:117], v[164:165], v[34:35]
	v_pk_fma_f32 v[34:35], v[118:119], v[166:167], v[34:35]
	v_pk_fma_f32 v[34:35], v[120:121], v[168:169], v[34:35]
	v_pk_fma_f32 v[34:35], v[122:123], v[170:171], v[34:35]
	v_pk_fma_f32 v[34:35], v[124:125], v[172:173], v[34:35]
	v_pk_fma_f32 v[34:35], v[126:127], v[174:175], v[34:35]
	s_waitcnt lgkmcnt(0)
	v_pk_fma_f32 v[38:39], v[112:113], v[0:1], v[38:39]
	v_pk_fma_f32 v[38:39], v[114:115], v[2:3], v[38:39]
	v_pk_fma_f32 v[38:39], v[116:117], v[4:5], v[38:39]
	v_pk_fma_f32 v[38:39], v[118:119], v[6:7], v[38:39]
	v_pk_fma_f32 v[38:39], v[120:121], v[56:57], v[38:39]
	v_pk_fma_f32 v[38:39], v[122:123], v[58:59], v[38:39]
	v_pk_fma_f32 v[38:39], v[124:125], v[60:61], v[38:39]
	v_pk_fma_f32 v[38:39], v[126:127], v[62:63], v[38:39]
	v_add_f32_e32 v14, v14, v15
	v_add_f32_e32 v15, v16, v17
	v_add_f32_e32 v16, v18, v19
	v_add_f32_e32 v17, v20, v21
	v_add_f32_e32 v18, v22, v23
	v_add_f32_e32 v19, v24, v25
	v_add_f32_e32 v20, v30, v31
	v_add_f32_e32 v21, v34, v35
	v_add_f32_e32 v29, v38, v39
	v_readlane_b32 s26, v254, 58
	s_mulk_i32 s26, 0x900
	v_readlane_b32 s27, v254, 59
	v_add_u32_e32 v0, s26, v27
	ds_write2st64_b32 v0, v14, v15 offset0:160 offset1:161
	ds_write2st64_b32 v0, v16, v17 offset0:162 offset1:163
	ds_write2st64_b32 v0, v18, v19 offset0:164 offset1:165
	ds_write2st64_b32 v0, v20, v21 offset0:166 offset1:167
	ds_write_b32 v0, v29 offset:43008
	s_waitcnt lgkmcnt(0)
	s_barrier
	s_and_saveexec_b64 s[26:27], s[42:43]
	s_cbranch_execz .LBB0_1069
	s_mul_i32 s30, s28, 0x2400
	s_add_i32 s30, s30, s24
	v_or_b32_e32 v0, s30, v244
	v_ashrrev_i32_e32 v1, 31, v0
	s_mul_i32 s28, s28, 9
	v_lshl_add_u64 v[0:1], v[0:1], 2, s[90:91]
	v_lshl_add_u64 v[2:3], s[24:25], 2, v[8:9]
	s_mov_b64 s[24:25], 0
	v_mov_b32_e32 v4, v182
